# phase-0 f32 input/weight conversion loads marked nt (read once)
# baseline (speedup 1.0000x reference)
.LBB0_20:
	s_abs_i32 s5, s68
	s_mul_hi_u32 s6, s5, s67
	s_mul_i32 s7, s6, s63
	s_sub_i32 s5, s5, s7
	s_ashr_i32 s4, s68, 31
	s_add_i32 s7, s6, 1
	s_sub_i32 s42, s5, s63
	s_cmp_ge_u32 s5, s63
	s_cselect_b32 s6, s7, s6
	s_cselect_b32 s5, s42, s5
	s_add_i32 s7, s6, 1
	s_cmp_ge_u32 s5, s63
	s_cselect_b32 s5, s7, s6
	s_xor_b32 s5, s5, s4
	s_sub_i32 s42, s5, s4
	s_mul_i32 s4, s42, s63
	s_sub_i32 s4, s68, s4
	s_lshl_b32 s69, s4, 6
	v_or_b32_e32 v14, s69, v18
	s_lshl_b32 s4, s42, 8
	v_ashrrev_i32_e32 v15, 31, v14
	v_cmp_gt_i32_e32 vcc, s62, v14
	v_or_b32_e32 v30, s4, v19
	v_lshl_add_u64 v[14:15], v[14:15], 2, s[38:39]
	v_mov_b32_e32 v16, 0
	v_mov_b32_e32 v17, 0
	s_and_saveexec_b64 s[6:7], vcc
	s_cbranch_execz .LBB0_22
	v_mad_i64_i32 v[32:33], s[44:45], v30, s62, 0
	v_lshl_add_u64 v[32:33], v[32:33], 2, v[14:15]
	global_load_dword v17, v[32:33], off nt
.LBB0_22:
	s_or_b64 exec, exec, s[6:7]
	s_and_saveexec_b64 s[6:7], vcc
	s_cbranch_execz .LBB0_24
	v_add_u32_e32 v16, 8, v30
	v_mad_i64_i32 v[32:33], s[44:45], v16, s62, 0
	v_lshl_add_u64 v[32:33], v[32:33], 2, v[14:15]
	global_load_dword v16, v[32:33], off nt
.LBB0_24:
	s_or_b64 exec, exec, s[6:7]
	v_mov_b32_e32 v31, 0
	v_mov_b32_e32 v32, 0
	s_and_saveexec_b64 s[6:7], vcc
	s_cbranch_execz .LBB0_26
	v_or_b32_e32 v32, 16, v30
	v_mad_i64_i32 v[32:33], s[44:45], v32, s62, 0
	v_lshl_add_u64 v[32:33], v[32:33], 2, v[14:15]
	global_load_dword v32, v[32:33], off nt
.LBB0_26:
	s_or_b64 exec, exec, s[6:7]
	s_and_saveexec_b64 s[6:7], vcc
	s_cbranch_execz .LBB0_28
	v_add_u32_e32 v31, 24, v30
	v_mad_i64_i32 v[34:35], s[44:45], v31, s62, 0
	v_lshl_add_u64 v[34:35], v[34:35], 2, v[14:15]
	global_load_dword v31, v[34:35], off nt
.LBB0_28:
	s_or_b64 exec, exec, s[6:7]
	v_mov_b32_e32 v33, 0
	v_mov_b32_e32 v34, 0
	s_and_saveexec_b64 s[6:7], vcc
	s_cbranch_execz .LBB0_30
	v_or_b32_e32 v34, 32, v30
	v_mad_i64_i32 v[34:35], s[44:45], v34, s62, 0
	v_lshl_add_u64 v[34:35], v[34:35], 2, v[14:15]
	global_load_dword v34, v[34:35], off nt
.LBB0_30:
	s_or_b64 exec, exec, s[6:7]
	s_and_saveexec_b64 s[6:7], vcc
	s_cbranch_execz .LBB0_32
	v_add_u32_e32 v33, 40, v30
	v_mad_i64_i32 v[36:37], s[44:45], v33, s62, 0
	v_lshl_add_u64 v[36:37], v[36:37], 2, v[14:15]
	global_load_dword v33, v[36:37], off nt
.LBB0_32:
	s_or_b64 exec, exec, s[6:7]
	v_mov_b32_e32 v35, 0
	v_mov_b32_e32 v36, 0
	s_and_saveexec_b64 s[6:7], vcc
	s_cbranch_execz .LBB0_34
	v_or_b32_e32 v36, 48, v30
	v_mad_i64_i32 v[36:37], s[44:45], v36, s62, 0
	v_lshl_add_u64 v[36:37], v[36:37], 2, v[14:15]
	global_load_dword v36, v[36:37], off nt
.LBB0_34:
	s_or_b64 exec, exec, s[6:7]
	s_and_saveexec_b64 s[6:7], vcc
	s_cbranch_execz .LBB0_36
	v_add_u32_e32 v35, 56, v30
	v_mad_i64_i32 v[38:39], s[44:45], v35, s62, 0
	v_lshl_add_u64 v[38:39], v[38:39], 2, v[14:15]
	global_load_dword v35, v[38:39], off nt
.LBB0_36:
	s_or_b64 exec, exec, s[6:7]
	v_mov_b32_e32 v37, 0
	v_mov_b32_e32 v38, 0
	s_and_saveexec_b64 s[6:7], vcc
	s_cbranch_execz .LBB0_38
	v_or_b32_e32 v38, 64, v30
	v_mad_i64_i32 v[38:39], s[44:45], v38, s62, 0
	v_lshl_add_u64 v[38:39], v[38:39], 2, v[14:15]
	global_load_dword v38, v[38:39], off nt
.LBB0_38:
	s_or_b64 exec, exec, s[6:7]
	s_and_saveexec_b64 s[6:7], vcc
	s_cbranch_execz .LBB0_40
	v_add_u32_e32 v37, 0x48, v30
	v_mad_i64_i32 v[40:41], s[44:45], v37, s62, 0
	v_lshl_add_u64 v[40:41], v[40:41], 2, v[14:15]
	global_load_dword v37, v[40:41], off nt
.LBB0_40:
	s_or_b64 exec, exec, s[6:7]
	v_mov_b32_e32 v39, 0
	v_mov_b32_e32 v40, 0
	s_and_saveexec_b64 s[6:7], vcc
	s_cbranch_execz .LBB0_42
	v_or_b32_e32 v40, 0x50, v30
	v_mad_i64_i32 v[40:41], s[44:45], v40, s62, 0
	v_lshl_add_u64 v[40:41], v[40:41], 2, v[14:15]
	global_load_dword v40, v[40:41], off nt
.LBB0_42:
	s_or_b64 exec, exec, s[6:7]
	s_and_saveexec_b64 s[6:7], vcc
	s_cbranch_execz .LBB0_44
	v_add_u32_e32 v39, 0x58, v30
	v_mad_i64_i32 v[42:43], s[44:45], v39, s62, 0
	v_lshl_add_u64 v[42:43], v[42:43], 2, v[14:15]
	global_load_dword v39, v[42:43], off nt
.LBB0_44:
	s_or_b64 exec, exec, s[6:7]
	v_mov_b32_e32 v41, 0
	v_mov_b32_e32 v42, 0
	s_and_saveexec_b64 s[6:7], vcc
	s_cbranch_execz .LBB0_46
	v_or_b32_e32 v42, 0x60, v30
	v_mad_i64_i32 v[42:43], s[44:45], v42, s62, 0
	v_lshl_add_u64 v[42:43], v[42:43], 2, v[14:15]
	global_load_dword v42, v[42:43], off nt
.LBB0_46:
	s_or_b64 exec, exec, s[6:7]
	s_and_saveexec_b64 s[6:7], vcc
	s_cbranch_execz .LBB0_48
	v_add_u32_e32 v41, 0x68, v30
	v_mad_i64_i32 v[44:45], s[44:45], v41, s62, 0
	v_lshl_add_u64 v[44:45], v[44:45], 2, v[14:15]
	global_load_dword v41, v[44:45], off nt
.LBB0_48:
	s_or_b64 exec, exec, s[6:7]
	v_mov_b32_e32 v43, 0
	v_mov_b32_e32 v44, 0
	s_and_saveexec_b64 s[6:7], vcc
	s_cbranch_execz .LBB0_50
	v_or_b32_e32 v44, 0x70, v30
	v_mad_i64_i32 v[44:45], s[44:45], v44, s62, 0
	v_lshl_add_u64 v[44:45], v[44:45], 2, v[14:15]
	global_load_dword v44, v[44:45], off nt
.LBB0_50:
	s_or_b64 exec, exec, s[6:7]
	s_and_saveexec_b64 s[6:7], vcc
	s_cbranch_execz .LBB0_52
	v_add_u32_e32 v43, 0x78, v30
	v_mad_i64_i32 v[46:47], s[44:45], v43, s62, 0
	v_lshl_add_u64 v[46:47], v[46:47], 2, v[14:15]
	global_load_dword v43, v[46:47], off nt
.LBB0_52:
	s_or_b64 exec, exec, s[6:7]
	v_mov_b32_e32 v45, 0
	v_mov_b32_e32 v46, 0
	s_and_saveexec_b64 s[6:7], vcc
	s_cbranch_execz .LBB0_54
	v_or_b32_e32 v46, 0x80, v30
	v_mad_i64_i32 v[46:47], s[44:45], v46, s62, 0
	v_lshl_add_u64 v[46:47], v[46:47], 2, v[14:15]
	global_load_dword v46, v[46:47], off nt
.LBB0_54:
	s_or_b64 exec, exec, s[6:7]
	s_and_saveexec_b64 s[6:7], vcc
	s_cbranch_execz .LBB0_56
	v_add_u32_e32 v45, 0x88, v30
	v_mad_i64_i32 v[48:49], s[44:45], v45, s62, 0
	v_lshl_add_u64 v[48:49], v[48:49], 2, v[14:15]
	global_load_dword v45, v[48:49], off nt
.LBB0_56:
	s_or_b64 exec, exec, s[6:7]
	v_mov_b32_e32 v47, 0
	v_mov_b32_e32 v48, 0
	s_and_saveexec_b64 s[6:7], vcc
	s_cbranch_execz .LBB0_58
	v_or_b32_e32 v48, 0x90, v30
	v_mad_i64_i32 v[48:49], s[44:45], v48, s62, 0
	v_lshl_add_u64 v[48:49], v[48:49], 2, v[14:15]
	global_load_dword v48, v[48:49], off nt
.LBB0_58:
	s_or_b64 exec, exec, s[6:7]
	s_and_saveexec_b64 s[6:7], vcc
	s_cbranch_execz .LBB0_60
	v_add_u32_e32 v47, 0x98, v30
	v_mad_i64_i32 v[50:51], s[44:45], v47, s62, 0
	v_lshl_add_u64 v[50:51], v[50:51], 2, v[14:15]
	global_load_dword v47, v[50:51], off nt
.LBB0_60:
	s_or_b64 exec, exec, s[6:7]
	v_mov_b32_e32 v49, 0
	v_mov_b32_e32 v50, 0
	s_and_saveexec_b64 s[6:7], vcc
	s_cbranch_execz .LBB0_62
	v_or_b32_e32 v50, 0xa0, v30
	v_mad_i64_i32 v[50:51], s[44:45], v50, s62, 0
	v_lshl_add_u64 v[50:51], v[50:51], 2, v[14:15]
	global_load_dword v50, v[50:51], off nt
.LBB0_62:
	s_or_b64 exec, exec, s[6:7]
	s_and_saveexec_b64 s[6:7], vcc
	s_cbranch_execz .LBB0_64
	v_add_u32_e32 v49, 0xa8, v30
	v_mad_i64_i32 v[52:53], s[44:45], v49, s62, 0
	v_lshl_add_u64 v[52:53], v[52:53], 2, v[14:15]
	global_load_dword v49, v[52:53], off nt
.LBB0_64:
	s_or_b64 exec, exec, s[6:7]
	v_mov_b32_e32 v51, 0
	v_mov_b32_e32 v52, 0
	s_and_saveexec_b64 s[6:7], vcc
	s_cbranch_execz .LBB0_66
	v_or_b32_e32 v52, 0xb0, v30
	v_mad_i64_i32 v[52:53], s[44:45], v52, s62, 0
	v_lshl_add_u64 v[52:53], v[52:53], 2, v[14:15]
	global_load_dword v52, v[52:53], off nt
.LBB0_66:
	s_or_b64 exec, exec, s[6:7]
	s_and_saveexec_b64 s[6:7], vcc
	s_cbranch_execz .LBB0_68
	v_add_u32_e32 v51, 0xb8, v30
	v_mad_i64_i32 v[54:55], s[44:45], v51, s62, 0
	v_lshl_add_u64 v[54:55], v[54:55], 2, v[14:15]
	global_load_dword v51, v[54:55], off nt
.LBB0_68:
	s_or_b64 exec, exec, s[6:7]
	v_mov_b32_e32 v53, 0
	v_mov_b32_e32 v54, 0
	s_and_saveexec_b64 s[6:7], vcc
	s_cbranch_execz .LBB0_70
	v_or_b32_e32 v54, 0xc0, v30
	v_mad_i64_i32 v[54:55], s[44:45], v54, s62, 0
	v_lshl_add_u64 v[54:55], v[54:55], 2, v[14:15]
	global_load_dword v54, v[54:55], off nt
.LBB0_70:
	s_or_b64 exec, exec, s[6:7]
	s_and_saveexec_b64 s[6:7], vcc
	s_cbranch_execz .LBB0_72
	v_add_u32_e32 v53, 0xc8, v30
	v_mad_i64_i32 v[56:57], s[44:45], v53, s62, 0
	v_lshl_add_u64 v[56:57], v[56:57], 2, v[14:15]
	global_load_dword v53, v[56:57], off nt
.LBB0_72:
	s_or_b64 exec, exec, s[6:7]
	v_mov_b32_e32 v55, 0
	v_mov_b32_e32 v56, 0
	s_and_saveexec_b64 s[6:7], vcc
	s_cbranch_execz .LBB0_74
	v_or_b32_e32 v56, 0xd0, v30
	v_mad_i64_i32 v[56:57], s[44:45], v56, s62, 0
	v_lshl_add_u64 v[56:57], v[56:57], 2, v[14:15]
	global_load_dword v56, v[56:57], off nt
.LBB0_74:
	s_or_b64 exec, exec, s[6:7]
	s_and_saveexec_b64 s[6:7], vcc
	s_cbranch_execz .LBB0_76
	v_add_u32_e32 v55, 0xd8, v30
	v_mad_i64_i32 v[58:59], s[44:45], v55, s62, 0
	v_lshl_add_u64 v[58:59], v[58:59], 2, v[14:15]
	global_load_dword v55, v[58:59], off nt
.LBB0_76:
	s_or_b64 exec, exec, s[6:7]
	v_mov_b32_e32 v57, 0
	v_mov_b32_e32 v58, 0
	s_and_saveexec_b64 s[6:7], vcc
	s_cbranch_execz .LBB0_78
	v_or_b32_e32 v58, 0xe0, v30
	v_mad_i64_i32 v[58:59], s[44:45], v58, s62, 0
	v_lshl_add_u64 v[58:59], v[58:59], 2, v[14:15]
	global_load_dword v58, v[58:59], off nt
.LBB0_78:
	s_or_b64 exec, exec, s[6:7]
	s_and_saveexec_b64 s[6:7], vcc
	s_cbranch_execz .LBB0_80
	v_add_u32_e32 v57, 0xe8, v30
	v_mad_i64_i32 v[60:61], s[44:45], v57, s62, 0
	v_lshl_add_u64 v[60:61], v[60:61], 2, v[14:15]
	global_load_dword v57, v[60:61], off nt
.LBB0_80:
	s_or_b64 exec, exec, s[6:7]
	v_mov_b32_e32 v59, 0
	v_mov_b32_e32 v60, 0
	s_and_saveexec_b64 s[6:7], vcc
	s_cbranch_execz .LBB0_82
	v_or_b32_e32 v60, 0xf0, v30
	v_mad_i64_i32 v[60:61], s[44:45], v60, s62, 0
	v_lshl_add_u64 v[60:61], v[60:61], 2, v[14:15]
	global_load_dword v60, v[60:61], off nt
.LBB0_82:
	s_or_b64 exec, exec, s[6:7]
	s_and_saveexec_b64 s[6:7], vcc
	s_cbranch_execz .LBB0_84
	v_add_u32_e32 v30, 0xf8, v30
	v_mad_i64_i32 v[62:63], s[44:45], v30, s62, 0
	v_lshl_add_u64 v[14:15], v[62:63], 2, v[14:15]
	global_load_dword v59, v[14:15], off nt

.LBB0_225:
	s_ashr_i32 s4, s44, 31
	s_lshr_b32 s4, s4, 29
	s_add_i32 s40, s44, s4
	s_and_b32 s4, s40, 0x3fffff8
	s_sub_i32 s4, s44, s4
	s_lshl_b32 s45, s4, 6
	s_lshl_b32 s40, s40, 5
	v_or_b32_e32 v14, s45, v18
	s_and_b32 s40, s40, 0xffffff00
	v_or_b32_e32 v16, s40, v19
	v_ashrrev_i32_e32 v15, 31, v14
	v_cmp_gt_i32_e64 s[4:5], s59, v14
	v_lshl_add_u64 v[14:15], v[14:15], 2, s[38:39]
	v_mov_b32_e32 v31, 0
	v_ashrrev_i32_e32 v17, 31, v16
	v_mov_b32_e32 v30, 0
	s_and_saveexec_b64 s[42:43], s[4:5]
	s_cbranch_execz .LBB0_227
	v_lshlrev_b64 v[32:33], 11, v[16:17]
	v_lshl_add_u64 v[32:33], v[14:15], 0, v[32:33]
	global_load_dword v30, v[32:33], off nt
.LBB0_227:
	s_or_b64 exec, exec, s[42:43]
	s_and_saveexec_b64 s[42:43], s[4:5]
	s_cbranch_execz .LBB0_229
	v_lshlrev_b64 v[32:33], 11, v[16:17]
	v_lshl_add_u64 v[32:33], v[14:15], 0, v[32:33]
	v_add_co_u32_e32 v32, vcc, 0x4000, v32
	s_nop 1
	v_addc_co_u32_e32 v33, vcc, 0, v33, vcc
	global_load_dword v31, v[32:33], off nt
.LBB0_229:
	s_or_b64 exec, exec, s[42:43]
	v_mov_b32_e32 v33, 0
	v_mov_b32_e32 v32, 0
	s_and_saveexec_b64 s[42:43], s[4:5]
	s_cbranch_execz .LBB0_231
	v_or_b32_e32 v34, 16, v16
	v_ashrrev_i32_e32 v35, 31, v34
	v_lshlrev_b64 v[34:35], 11, v[34:35]
	v_lshl_add_u64 v[34:35], v[14:15], 0, v[34:35]
	global_load_dword v32, v[34:35], off nt
.LBB0_231:
	s_or_b64 exec, exec, s[42:43]
	s_and_saveexec_b64 s[42:43], s[4:5]
	s_cbranch_execz .LBB0_233
	v_lshlrev_b64 v[34:35], 11, v[16:17]
	v_lshl_add_u64 v[34:35], v[14:15], 0, v[34:35]
	v_add_co_u32_e32 v34, vcc, 0xc000, v34
	s_nop 1
	v_addc_co_u32_e32 v35, vcc, 0, v35, vcc
	global_load_dword v33, v[34:35], off nt
.LBB0_233:
	s_or_b64 exec, exec, s[42:43]
	v_mov_b32_e32 v35, 0
	v_mov_b32_e32 v34, 0
	s_and_saveexec_b64 s[42:43], s[4:5]
	s_cbranch_execz .LBB0_235
	v_or_b32_e32 v36, 32, v16
	v_ashrrev_i32_e32 v37, 31, v36
	v_lshlrev_b64 v[36:37], 11, v[36:37]
	v_lshl_add_u64 v[36:37], v[14:15], 0, v[36:37]
	global_load_dword v34, v[36:37], off nt
.LBB0_235:
	s_or_b64 exec, exec, s[42:43]
	s_and_saveexec_b64 s[42:43], s[4:5]
	s_cbranch_execz .LBB0_237
	v_lshlrev_b64 v[36:37], 11, v[16:17]
	v_lshl_add_u64 v[36:37], v[14:15], 0, v[36:37]
	v_add_co_u32_e32 v36, vcc, 0x14000, v36
	s_nop 1
	v_addc_co_u32_e32 v37, vcc, 0, v37, vcc
	global_load_dword v35, v[36:37], off nt
.LBB0_237:
	s_or_b64 exec, exec, s[42:43]
	v_mov_b32_e32 v37, 0
	v_mov_b32_e32 v36, 0
	s_and_saveexec_b64 s[42:43], s[4:5]
	s_cbranch_execz .LBB0_239
	v_or_b32_e32 v38, 48, v16
	v_ashrrev_i32_e32 v39, 31, v38
	v_lshlrev_b64 v[38:39], 11, v[38:39]
	v_lshl_add_u64 v[38:39], v[14:15], 0, v[38:39]
	global_load_dword v36, v[38:39], off nt
.LBB0_239:
	s_or_b64 exec, exec, s[42:43]
	s_and_saveexec_b64 s[42:43], s[4:5]
	s_cbranch_execz .LBB0_241
	v_lshlrev_b64 v[38:39], 11, v[16:17]
	v_lshl_add_u64 v[38:39], v[14:15], 0, v[38:39]
	v_add_co_u32_e32 v38, vcc, 0x1c000, v38
	s_nop 1
	v_addc_co_u32_e32 v39, vcc, 0, v39, vcc
	global_load_dword v37, v[38:39], off nt
.LBB0_241:
	s_or_b64 exec, exec, s[42:43]
	v_mov_b32_e32 v39, 0
	v_mov_b32_e32 v38, 0
	s_and_saveexec_b64 s[42:43], s[4:5]
	s_cbranch_execz .LBB0_243
	v_or_b32_e32 v40, 64, v16
	v_ashrrev_i32_e32 v41, 31, v40
	v_lshlrev_b64 v[40:41], 11, v[40:41]
	v_lshl_add_u64 v[40:41], v[14:15], 0, v[40:41]
	global_load_dword v38, v[40:41], off nt
.LBB0_243:
	s_or_b64 exec, exec, s[42:43]
	s_and_saveexec_b64 s[42:43], s[4:5]
	s_cbranch_execz .LBB0_245
	v_lshlrev_b64 v[40:41], 11, v[16:17]
	v_lshl_add_u64 v[40:41], v[14:15], 0, v[40:41]
	v_add_co_u32_e32 v40, vcc, 0x24000, v40
	s_nop 1
	v_addc_co_u32_e32 v41, vcc, 0, v41, vcc
	global_load_dword v39, v[40:41], off nt
.LBB0_245:
	s_or_b64 exec, exec, s[42:43]
	v_mov_b32_e32 v41, 0
	v_mov_b32_e32 v40, 0
	s_and_saveexec_b64 s[42:43], s[4:5]
	s_cbranch_execz .LBB0_247
	v_or_b32_e32 v42, 0x50, v16
	v_ashrrev_i32_e32 v43, 31, v42
	v_lshlrev_b64 v[42:43], 11, v[42:43]
	v_lshl_add_u64 v[42:43], v[14:15], 0, v[42:43]
	global_load_dword v40, v[42:43], off nt
.LBB0_247:
	s_or_b64 exec, exec, s[42:43]
	s_and_saveexec_b64 s[42:43], s[4:5]
	s_cbranch_execz .LBB0_249
	v_lshlrev_b64 v[42:43], 11, v[16:17]
	v_lshl_add_u64 v[42:43], v[14:15], 0, v[42:43]
	v_add_co_u32_e32 v42, vcc, 0x2c000, v42
	s_nop 1
	v_addc_co_u32_e32 v43, vcc, 0, v43, vcc
	global_load_dword v41, v[42:43], off nt
.LBB0_249:
	s_or_b64 exec, exec, s[42:43]
	v_mov_b32_e32 v43, 0
	v_mov_b32_e32 v42, 0
	s_and_saveexec_b64 s[42:43], s[4:5]
	s_cbranch_execz .LBB0_251
	v_or_b32_e32 v44, 0x60, v16
	v_ashrrev_i32_e32 v45, 31, v44
	v_lshlrev_b64 v[44:45], 11, v[44:45]
	v_lshl_add_u64 v[44:45], v[14:15], 0, v[44:45]
	global_load_dword v42, v[44:45], off nt
.LBB0_251:
	s_or_b64 exec, exec, s[42:43]
	s_and_saveexec_b64 s[42:43], s[4:5]
	s_cbranch_execz .LBB0_253
	v_lshlrev_b64 v[44:45], 11, v[16:17]
	v_lshl_add_u64 v[44:45], v[14:15], 0, v[44:45]
	v_add_co_u32_e32 v44, vcc, 0x34000, v44
	s_nop 1
	v_addc_co_u32_e32 v45, vcc, 0, v45, vcc
	global_load_dword v43, v[44:45], off nt
.LBB0_253:
	s_or_b64 exec, exec, s[42:43]
	v_mov_b32_e32 v45, 0
	v_mov_b32_e32 v44, 0
	s_and_saveexec_b64 s[42:43], s[4:5]
	s_cbranch_execz .LBB0_255
	v_or_b32_e32 v46, 0x70, v16
	v_ashrrev_i32_e32 v47, 31, v46
	v_lshlrev_b64 v[46:47], 11, v[46:47]
	v_lshl_add_u64 v[46:47], v[14:15], 0, v[46:47]
	global_load_dword v44, v[46:47], off nt
.LBB0_255:
	s_or_b64 exec, exec, s[42:43]
	s_and_saveexec_b64 s[42:43], s[4:5]
	s_cbranch_execz .LBB0_257
	v_lshlrev_b64 v[46:47], 11, v[16:17]
	v_lshl_add_u64 v[46:47], v[14:15], 0, v[46:47]
	v_add_co_u32_e32 v46, vcc, 0x3c000, v46
	s_nop 1
	v_addc_co_u32_e32 v47, vcc, 0, v47, vcc
	global_load_dword v45, v[46:47], off nt
.LBB0_257:
	s_or_b64 exec, exec, s[42:43]
	v_mov_b32_e32 v47, 0
	v_mov_b32_e32 v46, 0
	s_and_saveexec_b64 s[42:43], s[4:5]
	s_cbranch_execz .LBB0_259
	v_or_b32_e32 v48, 0x80, v16
	v_ashrrev_i32_e32 v49, 31, v48
	v_lshlrev_b64 v[48:49], 11, v[48:49]
	v_lshl_add_u64 v[48:49], v[14:15], 0, v[48:49]
	global_load_dword v46, v[48:49], off nt
.LBB0_259:
	s_or_b64 exec, exec, s[42:43]
	s_and_saveexec_b64 s[42:43], s[4:5]
	s_cbranch_execz .LBB0_261
	v_lshlrev_b64 v[48:49], 11, v[16:17]
	v_lshl_add_u64 v[48:49], v[14:15], 0, v[48:49]
	v_add_co_u32_e32 v48, vcc, 0x44000, v48
	s_nop 1
	v_addc_co_u32_e32 v49, vcc, 0, v49, vcc
	global_load_dword v47, v[48:49], off nt
.LBB0_261:
	s_or_b64 exec, exec, s[42:43]
	v_mov_b32_e32 v49, 0
	v_mov_b32_e32 v48, 0
	s_and_saveexec_b64 s[42:43], s[4:5]
	s_cbranch_execz .LBB0_263
	v_or_b32_e32 v50, 0x90, v16
	v_ashrrev_i32_e32 v51, 31, v50
	v_lshlrev_b64 v[50:51], 11, v[50:51]
	v_lshl_add_u64 v[50:51], v[14:15], 0, v[50:51]
	global_load_dword v48, v[50:51], off nt
.LBB0_263:
	s_or_b64 exec, exec, s[42:43]
	s_and_saveexec_b64 s[42:43], s[4:5]
	s_cbranch_execz .LBB0_265
	v_lshlrev_b64 v[50:51], 11, v[16:17]
	v_lshl_add_u64 v[50:51], v[14:15], 0, v[50:51]
	v_add_co_u32_e32 v50, vcc, 0x4c000, v50
	s_nop 1
	v_addc_co_u32_e32 v51, vcc, 0, v51, vcc
	global_load_dword v49, v[50:51], off nt
.LBB0_265:
	s_or_b64 exec, exec, s[42:43]
	v_mov_b32_e32 v51, 0
	v_mov_b32_e32 v50, 0
	s_and_saveexec_b64 s[42:43], s[4:5]
	s_cbranch_execz .LBB0_267
	v_or_b32_e32 v52, 0xa0, v16
	v_ashrrev_i32_e32 v53, 31, v52
	v_lshlrev_b64 v[52:53], 11, v[52:53]
	v_lshl_add_u64 v[52:53], v[14:15], 0, v[52:53]
	global_load_dword v50, v[52:53], off nt
.LBB0_267:
	s_or_b64 exec, exec, s[42:43]
	s_and_saveexec_b64 s[42:43], s[4:5]
	s_cbranch_execz .LBB0_269
	v_lshlrev_b64 v[52:53], 11, v[16:17]
	v_lshl_add_u64 v[52:53], v[14:15], 0, v[52:53]
	v_add_co_u32_e32 v52, vcc, 0x54000, v52
	s_nop 1
	v_addc_co_u32_e32 v53, vcc, 0, v53, vcc
	global_load_dword v51, v[52:53], off nt
.LBB0_269:
	s_or_b64 exec, exec, s[42:43]
	v_mov_b32_e32 v53, 0
	v_mov_b32_e32 v52, 0
	s_and_saveexec_b64 s[42:43], s[4:5]
	s_cbranch_execz .LBB0_271
	v_or_b32_e32 v54, 0xb0, v16
	v_ashrrev_i32_e32 v55, 31, v54
	v_lshlrev_b64 v[54:55], 11, v[54:55]
	v_lshl_add_u64 v[54:55], v[14:15], 0, v[54:55]
	global_load_dword v52, v[54:55], off nt
.LBB0_271:
	s_or_b64 exec, exec, s[42:43]
	s_and_saveexec_b64 s[42:43], s[4:5]
	s_cbranch_execz .LBB0_273
	v_lshlrev_b64 v[54:55], 11, v[16:17]
	v_lshl_add_u64 v[54:55], v[14:15], 0, v[54:55]
	v_add_co_u32_e32 v54, vcc, 0x5c000, v54
	s_nop 1
	v_addc_co_u32_e32 v55, vcc, 0, v55, vcc
	global_load_dword v53, v[54:55], off nt
.LBB0_273:
	s_or_b64 exec, exec, s[42:43]
	v_mov_b32_e32 v55, 0
	v_mov_b32_e32 v54, 0
	s_and_saveexec_b64 s[42:43], s[4:5]
	s_cbranch_execz .LBB0_275
	v_or_b32_e32 v56, 0xc0, v16
	v_ashrrev_i32_e32 v57, 31, v56
	v_lshlrev_b64 v[56:57], 11, v[56:57]
	v_lshl_add_u64 v[56:57], v[14:15], 0, v[56:57]
	global_load_dword v54, v[56:57], off nt
.LBB0_275:
	s_or_b64 exec, exec, s[42:43]
	s_and_saveexec_b64 s[42:43], s[4:5]
	s_cbranch_execz .LBB0_277
	v_lshlrev_b64 v[56:57], 11, v[16:17]
	v_lshl_add_u64 v[56:57], v[14:15], 0, v[56:57]
	v_add_co_u32_e32 v56, vcc, 0x64000, v56
	s_nop 1
	v_addc_co_u32_e32 v57, vcc, 0, v57, vcc
	global_load_dword v55, v[56:57], off nt
.LBB0_277:
	s_or_b64 exec, exec, s[42:43]
	v_mov_b32_e32 v57, 0
	v_mov_b32_e32 v56, 0
	s_and_saveexec_b64 s[42:43], s[4:5]
	s_cbranch_execz .LBB0_279
	v_or_b32_e32 v58, 0xd0, v16
	v_ashrrev_i32_e32 v59, 31, v58
	v_lshlrev_b64 v[58:59], 11, v[58:59]
	v_lshl_add_u64 v[58:59], v[14:15], 0, v[58:59]
	global_load_dword v56, v[58:59], off nt
.LBB0_279:
	s_or_b64 exec, exec, s[42:43]
	s_and_saveexec_b64 s[42:43], s[4:5]
	s_cbranch_execz .LBB0_281
	v_lshlrev_b64 v[58:59], 11, v[16:17]
	v_lshl_add_u64 v[58:59], v[14:15], 0, v[58:59]
	v_add_co_u32_e32 v58, vcc, 0x6c000, v58
	s_nop 1
	v_addc_co_u32_e32 v59, vcc, 0, v59, vcc
	global_load_dword v57, v[58:59], off nt
.LBB0_281:
	s_or_b64 exec, exec, s[42:43]
	v_mov_b32_e32 v59, 0
	v_mov_b32_e32 v58, 0
	s_and_saveexec_b64 s[42:43], s[4:5]
	s_cbranch_execz .LBB0_283
	v_or_b32_e32 v60, 0xe0, v16
	v_ashrrev_i32_e32 v61, 31, v60
	v_lshlrev_b64 v[60:61], 11, v[60:61]
	v_lshl_add_u64 v[60:61], v[14:15], 0, v[60:61]
	global_load_dword v58, v[60:61], off nt
.LBB0_283:
	s_or_b64 exec, exec, s[42:43]
	s_and_saveexec_b64 s[42:43], s[4:5]
	s_cbranch_execz .LBB0_285
	v_lshlrev_b64 v[60:61], 11, v[16:17]
	v_lshl_add_u64 v[60:61], v[14:15], 0, v[60:61]
	v_add_co_u32_e32 v60, vcc, 0x74000, v60
	s_nop 1
	v_addc_co_u32_e32 v61, vcc, 0, v61, vcc
	global_load_dword v59, v[60:61], off nt
.LBB0_285:
	s_or_b64 exec, exec, s[42:43]
	v_mov_b32_e32 v17, 0
	v_mov_b32_e32 v60, 0
	s_and_saveexec_b64 s[42:43], s[4:5]
	s_cbranch_execz .LBB0_287
	v_or_b32_e32 v60, 0xf0, v16
	v_ashrrev_i32_e32 v61, 31, v60
	v_lshlrev_b64 v[60:61], 11, v[60:61]
	v_lshl_add_u64 v[60:61], v[14:15], 0, v[60:61]
	global_load_dword v60, v[60:61], off nt
.LBB0_287:
	s_or_b64 exec, exec, s[42:43]
	s_and_saveexec_b64 s[42:43], s[4:5]
	s_cbranch_execz .LBB0_289
	v_add_u32_e32 v16, 0xf8, v16
	v_ashrrev_i32_e32 v17, 31, v16
	v_lshlrev_b64 v[16:17], 11, v[16:17]
	v_lshl_add_u64 v[14:15], v[14:15], 0, v[16:17]
	global_load_dword v17, v[14:15], off nt

.LBB0_296:
	s_ashr_i32 s4, s42, 31
	s_lshr_b32 s4, s4, 28
	s_add_i32 s6, s42, s4
	s_and_b32 s4, s6, 0x3fffff0
	s_sub_i32 s4, s42, s4
	s_lshl_b32 s43, s4, 6
	s_lshl_b32 s6, s6, 4
	v_or_b32_e32 v14, s43, v18
	s_and_b32 s6, s6, 0xffffff00
	v_or_b32_e32 v16, s6, v19
	v_ashrrev_i32_e32 v15, 31, v14
	v_cmp_gt_i32_e64 s[4:5], s58, v14
	v_lshl_add_u64 v[14:15], v[14:15], 2, s[38:39]
	v_mov_b32_e32 v31, 0
	v_ashrrev_i32_e32 v17, 31, v16
	v_mov_b32_e32 v30, 0
	s_and_saveexec_b64 s[40:41], s[4:5]
	s_cbranch_execz .LBB0_298
	v_lshlrev_b64 v[32:33], 12, v[16:17]
	v_lshl_add_u64 v[32:33], v[14:15], 0, v[32:33]
	global_load_dword v30, v[32:33], off nt
.LBB0_298:
	s_or_b64 exec, exec, s[40:41]
	s_and_saveexec_b64 s[40:41], s[4:5]
	s_cbranch_execz .LBB0_300
	v_lshlrev_b64 v[32:33], 12, v[16:17]
	v_lshl_add_u64 v[32:33], v[14:15], 0, v[32:33]
	v_add_co_u32_e32 v32, vcc, 0x8000, v32
	s_nop 1
	v_addc_co_u32_e32 v33, vcc, 0, v33, vcc
	global_load_dword v31, v[32:33], off nt
.LBB0_300:
	s_or_b64 exec, exec, s[40:41]
	v_mov_b32_e32 v33, 0
	v_mov_b32_e32 v32, 0
	s_and_saveexec_b64 s[40:41], s[4:5]
	s_cbranch_execz .LBB0_302
	v_or_b32_e32 v34, 16, v16
	v_ashrrev_i32_e32 v35, 31, v34
	v_lshlrev_b64 v[34:35], 12, v[34:35]
	v_lshl_add_u64 v[34:35], v[14:15], 0, v[34:35]
	global_load_dword v32, v[34:35], off nt
.LBB0_302:
	s_or_b64 exec, exec, s[40:41]
	s_and_saveexec_b64 s[40:41], s[4:5]
	s_cbranch_execz .LBB0_304
	v_lshlrev_b64 v[34:35], 12, v[16:17]
	v_lshl_add_u64 v[34:35], v[14:15], 0, v[34:35]
	v_add_co_u32_e32 v34, vcc, 0x18000, v34
	s_nop 1
	v_addc_co_u32_e32 v35, vcc, 0, v35, vcc
	global_load_dword v33, v[34:35], off nt
.LBB0_304:
	s_or_b64 exec, exec, s[40:41]
	v_mov_b32_e32 v35, 0
	v_mov_b32_e32 v34, 0
	s_and_saveexec_b64 s[40:41], s[4:5]
	s_cbranch_execz .LBB0_306
	v_or_b32_e32 v36, 32, v16
	v_ashrrev_i32_e32 v37, 31, v36
	v_lshlrev_b64 v[36:37], 12, v[36:37]
	v_lshl_add_u64 v[36:37], v[14:15], 0, v[36:37]
	global_load_dword v34, v[36:37], off nt
.LBB0_306:
	s_or_b64 exec, exec, s[40:41]
	s_and_saveexec_b64 s[40:41], s[4:5]
	s_cbranch_execz .LBB0_308
	v_lshlrev_b64 v[36:37], 12, v[16:17]
	v_lshl_add_u64 v[36:37], v[14:15], 0, v[36:37]
	v_add_co_u32_e32 v36, vcc, 0x28000, v36
	s_nop 1
	v_addc_co_u32_e32 v37, vcc, 0, v37, vcc
	global_load_dword v35, v[36:37], off nt
.LBB0_308:
	s_or_b64 exec, exec, s[40:41]
	v_mov_b32_e32 v37, 0
	v_mov_b32_e32 v36, 0
	s_and_saveexec_b64 s[40:41], s[4:5]
	s_cbranch_execz .LBB0_310
	v_or_b32_e32 v38, 48, v16
	v_ashrrev_i32_e32 v39, 31, v38
	v_lshlrev_b64 v[38:39], 12, v[38:39]
	v_lshl_add_u64 v[38:39], v[14:15], 0, v[38:39]
	global_load_dword v36, v[38:39], off nt
.LBB0_310:
	s_or_b64 exec, exec, s[40:41]
	s_and_saveexec_b64 s[40:41], s[4:5]
	s_cbranch_execz .LBB0_312
	v_lshlrev_b64 v[38:39], 12, v[16:17]
	v_lshl_add_u64 v[38:39], v[14:15], 0, v[38:39]
	v_add_co_u32_e32 v38, vcc, 0x38000, v38
	s_nop 1
	v_addc_co_u32_e32 v39, vcc, 0, v39, vcc
	global_load_dword v37, v[38:39], off nt
.LBB0_312:
	s_or_b64 exec, exec, s[40:41]
	v_mov_b32_e32 v39, 0
	v_mov_b32_e32 v38, 0
	s_and_saveexec_b64 s[40:41], s[4:5]
	s_cbranch_execz .LBB0_314
	v_or_b32_e32 v40, 64, v16
	v_ashrrev_i32_e32 v41, 31, v40
	v_lshlrev_b64 v[40:41], 12, v[40:41]
	v_lshl_add_u64 v[40:41], v[14:15], 0, v[40:41]
	global_load_dword v38, v[40:41], off nt
.LBB0_314:
	s_or_b64 exec, exec, s[40:41]
	s_and_saveexec_b64 s[40:41], s[4:5]
	s_cbranch_execz .LBB0_316
	v_lshlrev_b64 v[40:41], 12, v[16:17]
	v_lshl_add_u64 v[40:41], v[14:15], 0, v[40:41]
	v_add_co_u32_e32 v40, vcc, 0x48000, v40
	s_nop 1
	v_addc_co_u32_e32 v41, vcc, 0, v41, vcc
	global_load_dword v39, v[40:41], off nt
.LBB0_316:
	s_or_b64 exec, exec, s[40:41]
	v_mov_b32_e32 v41, 0
	v_mov_b32_e32 v40, 0
	s_and_saveexec_b64 s[40:41], s[4:5]
	s_cbranch_execz .LBB0_318
	v_or_b32_e32 v42, 0x50, v16
	v_ashrrev_i32_e32 v43, 31, v42
	v_lshlrev_b64 v[42:43], 12, v[42:43]
	v_lshl_add_u64 v[42:43], v[14:15], 0, v[42:43]
	global_load_dword v40, v[42:43], off nt
.LBB0_318:
	s_or_b64 exec, exec, s[40:41]
	s_and_saveexec_b64 s[40:41], s[4:5]
	s_cbranch_execz .LBB0_320
	v_lshlrev_b64 v[42:43], 12, v[16:17]
	v_lshl_add_u64 v[42:43], v[14:15], 0, v[42:43]
	v_add_co_u32_e32 v42, vcc, 0x58000, v42
	s_nop 1
	v_addc_co_u32_e32 v43, vcc, 0, v43, vcc
	global_load_dword v41, v[42:43], off nt
.LBB0_320:
	s_or_b64 exec, exec, s[40:41]
	v_mov_b32_e32 v43, 0
	v_mov_b32_e32 v42, 0
	s_and_saveexec_b64 s[40:41], s[4:5]
	s_cbranch_execz .LBB0_322
	v_or_b32_e32 v44, 0x60, v16
	v_ashrrev_i32_e32 v45, 31, v44
	v_lshlrev_b64 v[44:45], 12, v[44:45]
	v_lshl_add_u64 v[44:45], v[14:15], 0, v[44:45]
	global_load_dword v42, v[44:45], off nt
.LBB0_322:
	s_or_b64 exec, exec, s[40:41]
	s_and_saveexec_b64 s[40:41], s[4:5]
	s_cbranch_execz .LBB0_324
	v_lshlrev_b64 v[44:45], 12, v[16:17]
	v_lshl_add_u64 v[44:45], v[14:15], 0, v[44:45]
	v_add_co_u32_e32 v44, vcc, 0x68000, v44
	s_nop 1
	v_addc_co_u32_e32 v45, vcc, 0, v45, vcc
	global_load_dword v43, v[44:45], off nt
.LBB0_324:
	s_or_b64 exec, exec, s[40:41]
	v_mov_b32_e32 v45, 0
	v_mov_b32_e32 v44, 0
	s_and_saveexec_b64 s[40:41], s[4:5]
	s_cbranch_execz .LBB0_326
	v_or_b32_e32 v46, 0x70, v16
	v_ashrrev_i32_e32 v47, 31, v46
	v_lshlrev_b64 v[46:47], 12, v[46:47]
	v_lshl_add_u64 v[46:47], v[14:15], 0, v[46:47]
	global_load_dword v44, v[46:47], off nt
.LBB0_326:
	s_or_b64 exec, exec, s[40:41]
	s_and_saveexec_b64 s[40:41], s[4:5]
	s_cbranch_execz .LBB0_328
	v_lshlrev_b64 v[46:47], 12, v[16:17]
	v_lshl_add_u64 v[46:47], v[14:15], 0, v[46:47]
	v_add_co_u32_e32 v46, vcc, 0x78000, v46
	s_nop 1
	v_addc_co_u32_e32 v47, vcc, 0, v47, vcc
	global_load_dword v45, v[46:47], off nt
.LBB0_328:
	s_or_b64 exec, exec, s[40:41]
	v_mov_b32_e32 v47, 0
	v_mov_b32_e32 v46, 0
	s_and_saveexec_b64 s[40:41], s[4:5]
	s_cbranch_execz .LBB0_330
	v_or_b32_e32 v48, 0x80, v16
	v_ashrrev_i32_e32 v49, 31, v48
	v_lshlrev_b64 v[48:49], 12, v[48:49]
	v_lshl_add_u64 v[48:49], v[14:15], 0, v[48:49]
	global_load_dword v46, v[48:49], off nt
.LBB0_330:
	s_or_b64 exec, exec, s[40:41]
	s_and_saveexec_b64 s[40:41], s[4:5]
	s_cbranch_execz .LBB0_332
	v_lshlrev_b64 v[48:49], 12, v[16:17]
	v_lshl_add_u64 v[48:49], v[14:15], 0, v[48:49]
	v_add_co_u32_e32 v48, vcc, 0x88000, v48
	s_nop 1
	v_addc_co_u32_e32 v49, vcc, 0, v49, vcc
	global_load_dword v47, v[48:49], off nt
.LBB0_332:
	s_or_b64 exec, exec, s[40:41]
	v_mov_b32_e32 v49, 0
	v_mov_b32_e32 v48, 0
	s_and_saveexec_b64 s[40:41], s[4:5]
	s_cbranch_execz .LBB0_334
	v_or_b32_e32 v50, 0x90, v16
	v_ashrrev_i32_e32 v51, 31, v50
	v_lshlrev_b64 v[50:51], 12, v[50:51]
	v_lshl_add_u64 v[50:51], v[14:15], 0, v[50:51]
	global_load_dword v48, v[50:51], off nt
.LBB0_334:
	s_or_b64 exec, exec, s[40:41]
	s_and_saveexec_b64 s[40:41], s[4:5]
	s_cbranch_execz .LBB0_336
	v_lshlrev_b64 v[50:51], 12, v[16:17]
	v_lshl_add_u64 v[50:51], v[14:15], 0, v[50:51]
	v_add_co_u32_e32 v50, vcc, 0x98000, v50
	s_nop 1
	v_addc_co_u32_e32 v51, vcc, 0, v51, vcc
	global_load_dword v49, v[50:51], off nt
.LBB0_336:
	s_or_b64 exec, exec, s[40:41]
	v_mov_b32_e32 v51, 0
	v_mov_b32_e32 v50, 0
	s_and_saveexec_b64 s[40:41], s[4:5]
	s_cbranch_execz .LBB0_338
	v_or_b32_e32 v52, 0xa0, v16
	v_ashrrev_i32_e32 v53, 31, v52
	v_lshlrev_b64 v[52:53], 12, v[52:53]
	v_lshl_add_u64 v[52:53], v[14:15], 0, v[52:53]
	global_load_dword v50, v[52:53], off nt
.LBB0_338:
	s_or_b64 exec, exec, s[40:41]
	s_and_saveexec_b64 s[40:41], s[4:5]
	s_cbranch_execz .LBB0_340
	v_lshlrev_b64 v[52:53], 12, v[16:17]
	v_lshl_add_u64 v[52:53], v[14:15], 0, v[52:53]
	v_add_co_u32_e32 v52, vcc, 0xa8000, v52
	s_nop 1
	v_addc_co_u32_e32 v53, vcc, 0, v53, vcc
	global_load_dword v51, v[52:53], off nt
.LBB0_340:
	s_or_b64 exec, exec, s[40:41]
	v_mov_b32_e32 v53, 0
	v_mov_b32_e32 v52, 0
	s_and_saveexec_b64 s[40:41], s[4:5]
	s_cbranch_execz .LBB0_342
	v_or_b32_e32 v54, 0xb0, v16
	v_ashrrev_i32_e32 v55, 31, v54
	v_lshlrev_b64 v[54:55], 12, v[54:55]
	v_lshl_add_u64 v[54:55], v[14:15], 0, v[54:55]
	global_load_dword v52, v[54:55], off nt
.LBB0_342:
	s_or_b64 exec, exec, s[40:41]
	s_and_saveexec_b64 s[40:41], s[4:5]
	s_cbranch_execz .LBB0_344
	v_lshlrev_b64 v[54:55], 12, v[16:17]
	v_lshl_add_u64 v[54:55], v[14:15], 0, v[54:55]
	v_add_co_u32_e32 v54, vcc, 0xb8000, v54
	s_nop 1
	v_addc_co_u32_e32 v55, vcc, 0, v55, vcc
	global_load_dword v53, v[54:55], off nt
.LBB0_344:
	s_or_b64 exec, exec, s[40:41]
	v_mov_b32_e32 v55, 0
	v_mov_b32_e32 v54, 0
	s_and_saveexec_b64 s[40:41], s[4:5]
	s_cbranch_execz .LBB0_346
	v_or_b32_e32 v56, 0xc0, v16
	v_ashrrev_i32_e32 v57, 31, v56
	v_lshlrev_b64 v[56:57], 12, v[56:57]
	v_lshl_add_u64 v[56:57], v[14:15], 0, v[56:57]
	global_load_dword v54, v[56:57], off nt
.LBB0_346:
	s_or_b64 exec, exec, s[40:41]
	s_and_saveexec_b64 s[40:41], s[4:5]
	s_cbranch_execz .LBB0_348
	v_lshlrev_b64 v[56:57], 12, v[16:17]
	v_lshl_add_u64 v[56:57], v[14:15], 0, v[56:57]
	v_add_co_u32_e32 v56, vcc, 0xc8000, v56
	s_nop 1
	v_addc_co_u32_e32 v57, vcc, 0, v57, vcc
	global_load_dword v55, v[56:57], off nt
.LBB0_348:
	s_or_b64 exec, exec, s[40:41]
	v_mov_b32_e32 v57, 0
	v_mov_b32_e32 v56, 0
	s_and_saveexec_b64 s[40:41], s[4:5]
	s_cbranch_execz .LBB0_350
	v_or_b32_e32 v58, 0xd0, v16
	v_ashrrev_i32_e32 v59, 31, v58
	v_lshlrev_b64 v[58:59], 12, v[58:59]
	v_lshl_add_u64 v[58:59], v[14:15], 0, v[58:59]
	global_load_dword v56, v[58:59], off nt
.LBB0_350:
	s_or_b64 exec, exec, s[40:41]
	s_and_saveexec_b64 s[40:41], s[4:5]
	s_cbranch_execz .LBB0_352
	v_lshlrev_b64 v[58:59], 12, v[16:17]
	v_lshl_add_u64 v[58:59], v[14:15], 0, v[58:59]
	v_add_co_u32_e32 v58, vcc, 0xd8000, v58
	s_nop 1
	v_addc_co_u32_e32 v59, vcc, 0, v59, vcc
	global_load_dword v57, v[58:59], off nt
.LBB0_352:
	s_or_b64 exec, exec, s[40:41]
	v_mov_b32_e32 v59, 0
	v_mov_b32_e32 v58, 0
	s_and_saveexec_b64 s[40:41], s[4:5]
	s_cbranch_execz .LBB0_354
	v_or_b32_e32 v60, 0xe0, v16
	v_ashrrev_i32_e32 v61, 31, v60
	v_lshlrev_b64 v[60:61], 12, v[60:61]
	v_lshl_add_u64 v[60:61], v[14:15], 0, v[60:61]
	global_load_dword v58, v[60:61], off nt
.LBB0_354:
	s_or_b64 exec, exec, s[40:41]
	s_and_saveexec_b64 s[40:41], s[4:5]
	s_cbranch_execz .LBB0_356
	v_lshlrev_b64 v[60:61], 12, v[16:17]
	v_lshl_add_u64 v[60:61], v[14:15], 0, v[60:61]
	v_add_co_u32_e32 v60, vcc, 0xe8000, v60
	s_nop 1
	v_addc_co_u32_e32 v61, vcc, 0, v61, vcc
	global_load_dword v59, v[60:61], off nt
.LBB0_356:
	s_or_b64 exec, exec, s[40:41]
	v_mov_b32_e32 v17, 0
	v_mov_b32_e32 v60, 0
	s_and_saveexec_b64 s[40:41], s[4:5]
	s_cbranch_execz .LBB0_358
	v_or_b32_e32 v60, 0xf0, v16
	v_ashrrev_i32_e32 v61, 31, v60
	v_lshlrev_b64 v[60:61], 12, v[60:61]
	v_lshl_add_u64 v[60:61], v[14:15], 0, v[60:61]
	global_load_dword v60, v[60:61], off nt
.LBB0_358:
	s_or_b64 exec, exec, s[40:41]
	s_and_saveexec_b64 s[40:41], s[4:5]
	s_cbranch_execz .LBB0_360
	v_add_u32_e32 v16, 0xf8, v16
	v_ashrrev_i32_e32 v17, 31, v16
	v_lshlrev_b64 v[16:17], 12, v[16:17]
	v_lshl_add_u64 v[14:15], v[14:15], 0, v[16:17]
	global_load_dword v17, v[14:15], off nt

.LBB0_367:
	s_mul_hi_i32 s38, s42, 0x2e8ba2e9
	s_lshr_b32 s39, s38, 31
	s_ashr_i32 s38, s38, 4
	s_add_i32 s38, s38, s39
	s_mul_i32 s39, s38, 0x58
	s_sub_i32 s39, s42, s39
	s_lshl_b32 s43, s39, 6
	v_or_b32_e32 v14, s43, v18
	s_lshl_b32 s38, s38, 8
	v_ashrrev_i32_e32 v15, 31, v14
	v_cmp_gt_i32_e32 vcc, s60, v14
	v_or_b32_e32 v30, s38, v19
	v_lshl_add_u64 v[14:15], v[14:15], 2, s[6:7]
	v_mov_b32_e32 v16, 0
	v_mov_b32_e32 v17, 0
	s_and_saveexec_b64 s[40:41], vcc
	s_cbranch_execz .LBB0_369
	v_mad_i64_i32 v[32:33], s[44:45], v30, s61, v[14:15]
	global_load_dword v17, v[32:33], off nt
.LBB0_369:
	s_or_b64 exec, exec, s[40:41]
	s_and_saveexec_b64 s[40:41], vcc
	s_cbranch_execz .LBB0_371
	v_add_u32_e32 v16, 8, v30
	v_mad_i64_i32 v[32:33], s[44:45], v16, s61, v[14:15]
	global_load_dword v16, v[32:33], off nt
.LBB0_371:
	s_or_b64 exec, exec, s[40:41]
	v_mov_b32_e32 v31, 0
	v_mov_b32_e32 v32, 0
	s_and_saveexec_b64 s[40:41], vcc
	s_cbranch_execz .LBB0_373
	v_or_b32_e32 v32, 16, v30
	v_mad_i64_i32 v[32:33], s[44:45], v32, s61, v[14:15]
	global_load_dword v32, v[32:33], off nt
.LBB0_373:
	s_or_b64 exec, exec, s[40:41]
	s_and_saveexec_b64 s[40:41], vcc
	s_cbranch_execz .LBB0_375
	v_add_u32_e32 v31, 24, v30
	v_mad_i64_i32 v[34:35], s[44:45], v31, s61, v[14:15]
	global_load_dword v31, v[34:35], off nt
.LBB0_375:
	s_or_b64 exec, exec, s[40:41]
	v_mov_b32_e32 v33, 0
	v_mov_b32_e32 v34, 0
	s_and_saveexec_b64 s[40:41], vcc
	s_cbranch_execz .LBB0_377
	v_or_b32_e32 v34, 32, v30
	v_mad_i64_i32 v[34:35], s[44:45], v34, s61, v[14:15]
	global_load_dword v34, v[34:35], off nt
.LBB0_377:
	s_or_b64 exec, exec, s[40:41]
	s_and_saveexec_b64 s[40:41], vcc
	s_cbranch_execz .LBB0_379
	v_add_u32_e32 v33, 40, v30
	v_mad_i64_i32 v[36:37], s[44:45], v33, s61, v[14:15]
	global_load_dword v33, v[36:37], off nt
.LBB0_379:
	s_or_b64 exec, exec, s[40:41]
	v_mov_b32_e32 v35, 0
	v_mov_b32_e32 v36, 0
	s_and_saveexec_b64 s[40:41], vcc
	s_cbranch_execz .LBB0_381
	v_or_b32_e32 v36, 48, v30
	v_mad_i64_i32 v[36:37], s[44:45], v36, s61, v[14:15]
	global_load_dword v36, v[36:37], off nt
.LBB0_381:
	s_or_b64 exec, exec, s[40:41]
	s_and_saveexec_b64 s[40:41], vcc
	s_cbranch_execz .LBB0_383
	v_add_u32_e32 v35, 56, v30
	v_mad_i64_i32 v[38:39], s[44:45], v35, s61, v[14:15]
	global_load_dword v35, v[38:39], off nt
.LBB0_383:
	s_or_b64 exec, exec, s[40:41]
	v_mov_b32_e32 v37, 0
	v_mov_b32_e32 v38, 0
	s_and_saveexec_b64 s[40:41], vcc
	s_cbranch_execz .LBB0_385
	v_or_b32_e32 v38, 64, v30
	v_mad_i64_i32 v[38:39], s[44:45], v38, s61, v[14:15]
	global_load_dword v38, v[38:39], off nt
.LBB0_385:
	s_or_b64 exec, exec, s[40:41]
	s_and_saveexec_b64 s[40:41], vcc
	s_cbranch_execz .LBB0_387
	v_add_u32_e32 v37, 0x48, v30
	v_mad_i64_i32 v[40:41], s[44:45], v37, s61, v[14:15]
	global_load_dword v37, v[40:41], off nt
.LBB0_387:
	s_or_b64 exec, exec, s[40:41]
	v_mov_b32_e32 v39, 0
	v_mov_b32_e32 v40, 0
	s_and_saveexec_b64 s[40:41], vcc
	s_cbranch_execz .LBB0_389
	v_or_b32_e32 v40, 0x50, v30
	v_mad_i64_i32 v[40:41], s[44:45], v40, s61, v[14:15]
	global_load_dword v40, v[40:41], off nt
.LBB0_389:
	s_or_b64 exec, exec, s[40:41]
	s_and_saveexec_b64 s[40:41], vcc
	s_cbranch_execz .LBB0_391
	v_add_u32_e32 v39, 0x58, v30
	v_mad_i64_i32 v[42:43], s[44:45], v39, s61, v[14:15]
	global_load_dword v39, v[42:43], off nt
.LBB0_391:
	s_or_b64 exec, exec, s[40:41]
	v_mov_b32_e32 v41, 0
	v_mov_b32_e32 v42, 0
	s_and_saveexec_b64 s[40:41], vcc
	s_cbranch_execz .LBB0_393
	v_or_b32_e32 v42, 0x60, v30
	v_mad_i64_i32 v[42:43], s[44:45], v42, s61, v[14:15]
	global_load_dword v42, v[42:43], off nt
.LBB0_393:
	s_or_b64 exec, exec, s[40:41]
	s_and_saveexec_b64 s[40:41], vcc
	s_cbranch_execz .LBB0_395
	v_add_u32_e32 v41, 0x68, v30
	v_mad_i64_i32 v[44:45], s[44:45], v41, s61, v[14:15]
	global_load_dword v41, v[44:45], off nt
.LBB0_395:
	s_or_b64 exec, exec, s[40:41]
	v_mov_b32_e32 v43, 0
	v_mov_b32_e32 v44, 0
	s_and_saveexec_b64 s[40:41], vcc
	s_cbranch_execz .LBB0_397
	v_or_b32_e32 v44, 0x70, v30
	v_mad_i64_i32 v[44:45], s[44:45], v44, s61, v[14:15]
	global_load_dword v44, v[44:45], off nt
.LBB0_397:
	s_or_b64 exec, exec, s[40:41]
	s_and_saveexec_b64 s[40:41], vcc
	s_cbranch_execz .LBB0_399
	v_add_u32_e32 v43, 0x78, v30
	v_mad_i64_i32 v[46:47], s[44:45], v43, s61, v[14:15]
	global_load_dword v43, v[46:47], off nt
.LBB0_399:
	s_or_b64 exec, exec, s[40:41]
	v_mov_b32_e32 v45, 0
	v_mov_b32_e32 v46, 0
	s_and_saveexec_b64 s[40:41], vcc
	s_cbranch_execz .LBB0_401
	v_or_b32_e32 v46, 0x80, v30
	v_mad_i64_i32 v[46:47], s[44:45], v46, s61, v[14:15]
	global_load_dword v46, v[46:47], off nt
.LBB0_401:
	s_or_b64 exec, exec, s[40:41]
	s_and_saveexec_b64 s[40:41], vcc
	s_cbranch_execz .LBB0_403
	v_add_u32_e32 v45, 0x88, v30
	v_mad_i64_i32 v[48:49], s[44:45], v45, s61, v[14:15]
	global_load_dword v45, v[48:49], off nt
.LBB0_403:
	s_or_b64 exec, exec, s[40:41]
	v_mov_b32_e32 v47, 0
	v_mov_b32_e32 v48, 0
	s_and_saveexec_b64 s[40:41], vcc
	s_cbranch_execz .LBB0_405
	v_or_b32_e32 v48, 0x90, v30
	v_mad_i64_i32 v[48:49], s[44:45], v48, s61, v[14:15]
	global_load_dword v48, v[48:49], off nt
.LBB0_405:
	s_or_b64 exec, exec, s[40:41]
	s_and_saveexec_b64 s[40:41], vcc
	s_cbranch_execz .LBB0_407
	v_add_u32_e32 v47, 0x98, v30
	v_mad_i64_i32 v[50:51], s[44:45], v47, s61, v[14:15]
	global_load_dword v47, v[50:51], off nt
.LBB0_407:
	s_or_b64 exec, exec, s[40:41]
	v_mov_b32_e32 v49, 0
	v_mov_b32_e32 v50, 0
	s_and_saveexec_b64 s[40:41], vcc
	s_cbranch_execz .LBB0_409
	v_or_b32_e32 v50, 0xa0, v30
	v_mad_i64_i32 v[50:51], s[44:45], v50, s61, v[14:15]
	global_load_dword v50, v[50:51], off nt
.LBB0_409:
	s_or_b64 exec, exec, s[40:41]
	s_and_saveexec_b64 s[40:41], vcc
	s_cbranch_execz .LBB0_411
	v_add_u32_e32 v49, 0xa8, v30
	v_mad_i64_i32 v[52:53], s[44:45], v49, s61, v[14:15]
	global_load_dword v49, v[52:53], off nt
.LBB0_411:
	s_or_b64 exec, exec, s[40:41]
	v_mov_b32_e32 v51, 0
	v_mov_b32_e32 v52, 0
	s_and_saveexec_b64 s[40:41], vcc
	s_cbranch_execz .LBB0_413
	v_or_b32_e32 v52, 0xb0, v30
	v_mad_i64_i32 v[52:53], s[44:45], v52, s61, v[14:15]
	global_load_dword v52, v[52:53], off nt
.LBB0_413:
	s_or_b64 exec, exec, s[40:41]
	s_and_saveexec_b64 s[40:41], vcc
	s_cbranch_execz .LBB0_415
	v_add_u32_e32 v51, 0xb8, v30
	v_mad_i64_i32 v[54:55], s[44:45], v51, s61, v[14:15]
	global_load_dword v51, v[54:55], off nt
.LBB0_415:
	s_or_b64 exec, exec, s[40:41]
	v_mov_b32_e32 v53, 0
	v_mov_b32_e32 v54, 0
	s_and_saveexec_b64 s[40:41], vcc
	s_cbranch_execz .LBB0_417
	v_or_b32_e32 v54, 0xc0, v30
	v_mad_i64_i32 v[54:55], s[44:45], v54, s61, v[14:15]
	global_load_dword v54, v[54:55], off nt
.LBB0_417:
	s_or_b64 exec, exec, s[40:41]
	s_and_saveexec_b64 s[40:41], vcc
	s_cbranch_execz .LBB0_419
	v_add_u32_e32 v53, 0xc8, v30
	v_mad_i64_i32 v[56:57], s[44:45], v53, s61, v[14:15]
	global_load_dword v53, v[56:57], off nt
.LBB0_419:
	s_or_b64 exec, exec, s[40:41]
	v_mov_b32_e32 v55, 0
	v_mov_b32_e32 v56, 0
	s_and_saveexec_b64 s[40:41], vcc
	s_cbranch_execz .LBB0_421
	v_or_b32_e32 v56, 0xd0, v30
	v_mad_i64_i32 v[56:57], s[44:45], v56, s61, v[14:15]
	global_load_dword v56, v[56:57], off nt
.LBB0_421:
	s_or_b64 exec, exec, s[40:41]
	s_and_saveexec_b64 s[40:41], vcc
	s_cbranch_execz .LBB0_423
	v_add_u32_e32 v55, 0xd8, v30
	v_mad_i64_i32 v[58:59], s[44:45], v55, s61, v[14:15]
	global_load_dword v55, v[58:59], off nt
.LBB0_423:
	s_or_b64 exec, exec, s[40:41]
	v_mov_b32_e32 v57, 0
	v_mov_b32_e32 v58, 0
	s_and_saveexec_b64 s[40:41], vcc
	s_cbranch_execz .LBB0_425
	v_or_b32_e32 v58, 0xe0, v30
	v_mad_i64_i32 v[58:59], s[44:45], v58, s61, v[14:15]
	global_load_dword v58, v[58:59], off nt
.LBB0_425:
	s_or_b64 exec, exec, s[40:41]
	s_and_saveexec_b64 s[40:41], vcc
	s_cbranch_execz .LBB0_427
	v_add_u32_e32 v57, 0xe8, v30
	v_mad_i64_i32 v[60:61], s[44:45], v57, s61, v[14:15]
	global_load_dword v57, v[60:61], off nt
.LBB0_427:
	s_or_b64 exec, exec, s[40:41]
	v_mov_b32_e32 v59, 0
	v_mov_b32_e32 v60, 0
	s_and_saveexec_b64 s[40:41], vcc
	s_cbranch_execz .LBB0_429
	v_or_b32_e32 v60, 0xf0, v30
	v_mad_i64_i32 v[60:61], s[44:45], v60, s61, v[14:15]
	global_load_dword v60, v[60:61], off nt
.LBB0_429:
	s_or_b64 exec, exec, s[40:41]
	s_and_saveexec_b64 s[40:41], vcc
	s_cbranch_execz .LBB0_431
	v_add_u32_e32 v30, 0xf8, v30
	v_mad_i64_i32 v[14:15], s[44:45], v30, s61, v[14:15]
	global_load_dword v59, v[14:15], off nt

.LBB0_444:
	s_ashr_i32 s4, s42, 31
	s_lshr_b32 s4, s4, 28
	s_add_i32 s38, s42, s4
	s_and_b32 s4, s38, 0x3fffff0
	s_sub_i32 s4, s42, s4
	s_lshl_b32 s43, s4, 6
	s_lshl_b32 s38, s38, 4
	v_or_b32_e32 v14, s43, v18
	s_and_b32 s38, s38, 0xffffff00
	v_or_b32_e32 v16, s38, v19
	v_ashrrev_i32_e32 v15, 31, v14
	v_cmp_gt_i32_e64 s[4:5], s58, v14
	v_lshl_add_u64 v[14:15], v[14:15], 2, s[6:7]
	v_mov_b32_e32 v31, 0
	v_ashrrev_i32_e32 v17, 31, v16
	v_mov_b32_e32 v30, 0
	s_and_saveexec_b64 s[40:41], s[4:5]
	s_cbranch_execz .LBB0_446
	v_lshlrev_b64 v[32:33], 12, v[16:17]
	v_lshl_add_u64 v[32:33], v[14:15], 0, v[32:33]
	global_load_dword v30, v[32:33], off nt
